# attention S-phase: 8 K-fragment ds_reads per tile issued together into free quads, MFMAs behind counted lgkmcnt (was 40 serialized read-wait-mfma)
# speedup vs baseline: 1.0089x; 1.0089x over previous
; #define LAS __attribute__((address_space(3)))
; #define MFMA32(a, b, c) __builtin_amdgcn_mfma_f32_32x32x16_bf16((a), (b), (c), 0, 0, 0)
; __device__ __forceinline__ void phase_attn_items(const Params& P, LAS unsigned char* lds) {
;     ...
;         f32x16 S[5];
; #pragma unroll
;         for (int kt = 0; kt < 5; ++kt) {
;             const int T = qt + kt - 2; const bool tv = (T >= 0) && (T < ntile);
;             f32x16 s;
; #pragma unroll
;             for (int i = 0; i < 16; ++i) s[i] = 0.f;
;             if (tv) {
;                 const LAS unsigned char* kl = lds + (wave + kt) * 8192;
;                 bf16x8 kf[8];
; #pragma unroll
;                 for (int ks = 0; ks < 8; ++ks) kf[ks] = *(const LAS bf16x8*)(kl + off_b(ql, 2 * ks + h));
; #pragma unroll
;                 for (int ks = 0; ks < 8; ++ks) s = MFMA32(kf[ks], qf[ks], s);
;             }
;             S[kt] = s;
;         }
.LBB0_174:
	s_add_i32 s2, s27, 2
	s_cmp_lt_i32 s13, s2
	s_cselect_b64 s[2:3], -1, 0
	s_cmp_gt_i32 s13, 1
	s_cselect_b64 s[24:25], -1, 0
	v_lshlrev_b32_e32 v3, 2, v165
	v_bfe_u32 v0, v174, 2, 2
	s_and_b64 s[50:51], s[24:25], s[2:3]
	v_and_or_b32 v3, v3, 12, v0
	v_lshl_add_u32 v4, v165, 8, 0
	v_cndmask_b32_e64 v5, 0, 1, s[50:51]
	v_readlane_b32 s2, v247, 14
	v_cmp_ne_u32_e64 s[40:41], 1, v5
	v_add_u32_e32 v5, 2, v164
	v_add_u32_e32 v175, s2, v4
	v_xor_b32_e32 v4, v3, v164
	v_add_u32_e32 v6, 4, v164
	v_add_u32_e32 v7, 6, v164
	v_add_u32_e32 v8, 8, v164
	v_add_u32_e32 v9, 10, v164
	v_add_u32_e32 v10, 12, v164
	v_add_u32_e32 v11, 14, v164
	s_andn2_b64 vcc, exec, s[50:51]
	v_lshl_add_u32 v189, v4, 4, v175
	v_xor_b32_e32 v190, v3, v5
	v_xor_b32_e32 v188, v3, v6
	v_xor_b32_e32 v187, v3, v7
	v_xor_b32_e32 v186, v3, v8
	v_xor_b32_e32 v185, v3, v9
	v_xor_b32_e32 v177, v3, v10
	v_xor_b32_e32 v176, v3, v11
	v_mov_b32_e32 v3, 0
	v_mov_b32_e32 v4, 0
	v_mov_b32_e32 v5, 0
	v_mov_b32_e32 v6, 0
	v_mov_b32_e32 v7, 0
	v_mov_b32_e32 v8, 0
	v_mov_b32_e32 v9, 0
	v_mov_b32_e32 v10, 0
	v_mov_b32_e32 v11, 0
	v_mov_b32_e32 v12, 0
	v_mov_b32_e32 v13, 0
	v_mov_b32_e32 v14, 0
	v_mov_b32_e32 v15, 0
	v_mov_b32_e32 v16, 0
	v_mov_b32_e32 v17, 0
	s_mov_b32 s94, s5
	s_mov_b64 s[96:97], s[68:69]
	s_waitcnt lgkmcnt(0)
	s_barrier
	s_cbranch_vccnz .LBB0_176
	ds_read_b128 v[208:211], v189
	v_lshl_add_u32 v240, v190, 4, v175
	ds_read_b128 v[212:215], v240
	v_lshl_add_u32 v240, v188, 4, v175
	ds_read_b128 v[216:219], v240
	v_lshl_add_u32 v240, v187, 4, v175
	ds_read_b128 v[220:223], v240
	v_lshl_add_u32 v240, v186, 4, v175
	ds_read_b128 v[224:227], v240
	v_lshl_add_u32 v240, v185, 4, v175
	ds_read_b128 v[228:231], v240
	v_lshl_add_u32 v240, v177, 4, v175
	ds_read_b128 v[232:235], v240
	v_lshl_add_u32 v240, v176, 4, v175
	ds_read_b128 v[236:239], v240
	s_waitcnt lgkmcnt(7)
	v_mfma_f32_32x32x16_bf16 v[2:17], v[208:211], v[158:161], 0
	s_waitcnt lgkmcnt(6)
	v_mfma_f32_32x32x16_bf16 v[2:17], v[212:215], v[154:157], v[2:17]
	s_waitcnt lgkmcnt(5)
	v_mfma_f32_32x32x16_bf16 v[2:17], v[216:219], v[150:153], v[2:17]
	s_waitcnt lgkmcnt(4)
	v_mfma_f32_32x32x16_bf16 v[2:17], v[220:223], v[146:149], v[2:17]
	s_waitcnt lgkmcnt(3)
	v_mfma_f32_32x32x16_bf16 v[2:17], v[224:227], v[142:145], v[2:17]
	s_waitcnt lgkmcnt(2)
	v_mfma_f32_32x32x16_bf16 v[2:17], v[228:231], v[138:141], v[2:17]
	s_waitcnt lgkmcnt(1)
	v_mfma_f32_32x32x16_bf16 v[2:17], v[232:235], v[134:137], v[2:17]
	s_waitcnt lgkmcnt(0)
	v_mfma_f32_32x32x16_bf16 v[2:17], v[236:239], v[130:133], v[2:17]
.LBB0_176:
	s_cmp_le_i32 s13, s27
	s_cselect_b64 s[2:3], -1, 0
	s_cmp_gt_i32 s13, 0
	s_cselect_b64 s[24:25], -1, 0
	s_and_b64 s[52:53], s[24:25], s[2:3]
	v_cndmask_b32_e64 v19, 0, 1, s[52:53]
	v_mov_b32_e32 v18, 0
	v_cmp_ne_u32_e64 s[42:43], 1, v19
	s_andn2_b64 vcc, exec, s[52:53]
	v_mov_b32_e32 v34, 0
	v_mov_b32_e32 v35, 0
	v_mov_b32_e32 v36, 0
	v_mov_b32_e32 v37, 0
	v_mov_b32_e32 v38, 0
	v_mov_b32_e32 v39, 0
	v_mov_b32_e32 v40, 0
	v_mov_b32_e32 v41, 0
	v_mov_b32_e32 v42, 0
	v_mov_b32_e32 v43, 0
	v_mov_b32_e32 v44, 0
	v_mov_b32_e32 v45, 0
	v_mov_b32_e32 v46, 0
	v_mov_b32_e32 v47, 0
	v_mov_b32_e32 v48, 0
	v_mov_b32_e32 v49, 0
	s_mov_b64 s[68:69], s[86:87]
	s_mov_b32 s95, s88
	s_cbranch_vccnz .LBB0_178
	ds_read_b128 v[208:211], v189 offset:8192
	v_lshl_add_u32 v240, v190, 4, v175
	ds_read_b128 v[212:215], v240 offset:8192
	v_lshl_add_u32 v240, v188, 4, v175
	ds_read_b128 v[216:219], v240 offset:8192
	v_lshl_add_u32 v240, v187, 4, v175
	ds_read_b128 v[220:223], v240 offset:8192
	v_lshl_add_u32 v240, v186, 4, v175
	ds_read_b128 v[224:227], v240 offset:8192
	v_lshl_add_u32 v240, v185, 4, v175
	ds_read_b128 v[228:231], v240 offset:8192
	v_lshl_add_u32 v240, v177, 4, v175
	ds_read_b128 v[232:235], v240 offset:8192
	v_lshl_add_u32 v240, v176, 4, v175
	ds_read_b128 v[236:239], v240 offset:8192
	s_waitcnt lgkmcnt(7)
	v_mfma_f32_32x32x16_bf16 v[34:49], v[208:211], v[158:161], 0
	s_waitcnt lgkmcnt(6)
	v_mfma_f32_32x32x16_bf16 v[34:49], v[212:215], v[154:157], v[34:49]
	s_waitcnt lgkmcnt(5)
	v_mfma_f32_32x32x16_bf16 v[34:49], v[216:219], v[150:153], v[34:49]
	s_waitcnt lgkmcnt(4)
	v_mfma_f32_32x32x16_bf16 v[34:49], v[220:223], v[146:149], v[34:49]
	s_waitcnt lgkmcnt(3)
	v_mfma_f32_32x32x16_bf16 v[34:49], v[224:227], v[142:145], v[34:49]
	s_waitcnt lgkmcnt(2)
	v_mfma_f32_32x32x16_bf16 v[34:49], v[228:231], v[138:141], v[34:49]
	s_waitcnt lgkmcnt(1)
	v_mfma_f32_32x32x16_bf16 v[34:49], v[232:235], v[134:137], v[34:49]
	s_waitcnt lgkmcnt(0)
	v_mfma_f32_32x32x16_bf16 v[34:49], v[236:239], v[130:133], v[34:49]
; #define LAS __attribute__((address_space(3)))
; #define MFMA32(a, b, c) __builtin_amdgcn_mfma_f32_32x32x16_bf16((a), (b), (c), 0, 0, 0)
; __device__ __forceinline__ void phase_attn_items(const Params& P, LAS unsigned char* lds) {
;     ...
;         f32x16 S[5];
; #pragma unroll
;         for (int kt = 0; kt < 5; ++kt) {
;             const int T = qt + kt - 2; const bool tv = (T >= 0) && (T < ntile);
;             f32x16 s;
; #pragma unroll
;             for (int i = 0; i < 16; ++i) s[i] = 0.f;
;             if (tv) {
;                 const LAS unsigned char* kl = lds + (wave + kt) * 8192;
;                 bf16x8 kf[8];
; #pragma unroll
;                 for (int ks = 0; ks < 8; ++ks) kf[ks] = *(const LAS bf16x8*)(kl + off_b(ql, 2 * ks + h));
; #pragma unroll
;                 for (int ks = 0; ks < 8; ++ks) s = MFMA32(kf[ks], qf[ks], s);
;             }
;             S[kt] = s;
;         }
.LBB0_178:
	s_cmp_lt_i32 s13, s27
	s_cselect_b64 s[2:3], -1, 0
	s_cmp_gt_i32 s13, -1
	s_cselect_b64 s[24:25], -1, 0
	s_and_b64 s[54:55], s[24:25], s[2:3]
	v_cndmask_b32_e64 v19, 0, 1, s[54:55]
	v_readlane_b32 s86, v252, 38
	v_cmp_ne_u32_e64 s[44:45], 1, v19
	s_andn2_b64 vcc, exec, s[54:55]
	v_mov_b32_e32 v19, 0
	v_mov_b32_e32 v20, 0
	v_mov_b32_e32 v21, 0
	v_mov_b32_e32 v22, 0
	v_mov_b32_e32 v23, 0
	v_mov_b32_e32 v24, 0
	v_mov_b32_e32 v25, 0
	v_mov_b32_e32 v26, 0
	v_mov_b32_e32 v27, 0
	v_mov_b32_e32 v28, 0
	v_mov_b32_e32 v29, 0
	v_mov_b32_e32 v30, 0
	v_mov_b32_e32 v31, 0
	v_mov_b32_e32 v32, 0
	v_mov_b32_e32 v33, 0
	v_readlane_b32 s87, v252, 39
	s_mov_b64 s[88:89], s[36:37]
	s_cbranch_vccnz .LBB0_180
	ds_read_b128 v[208:211], v189 offset:16384
	v_lshl_add_u32 v240, v190, 4, v175
	ds_read_b128 v[212:215], v240 offset:16384
	v_lshl_add_u32 v240, v188, 4, v175
	ds_read_b128 v[216:219], v240 offset:16384
	v_lshl_add_u32 v240, v187, 4, v175
	ds_read_b128 v[220:223], v240 offset:16384
	v_lshl_add_u32 v240, v186, 4, v175
	ds_read_b128 v[224:227], v240 offset:16384
	v_lshl_add_u32 v240, v185, 4, v175
	ds_read_b128 v[228:231], v240 offset:16384
	v_lshl_add_u32 v240, v177, 4, v175
	ds_read_b128 v[232:235], v240 offset:16384
	v_lshl_add_u32 v240, v176, 4, v175
	ds_read_b128 v[236:239], v240 offset:16384
	s_waitcnt lgkmcnt(7)
	v_mfma_f32_32x32x16_bf16 v[18:33], v[208:211], v[158:161], 0
	s_waitcnt lgkmcnt(6)
	v_mfma_f32_32x32x16_bf16 v[18:33], v[212:215], v[154:157], v[18:33]
	s_waitcnt lgkmcnt(5)
	v_mfma_f32_32x32x16_bf16 v[18:33], v[216:219], v[150:153], v[18:33]
	s_waitcnt lgkmcnt(4)
	v_mfma_f32_32x32x16_bf16 v[18:33], v[220:223], v[146:149], v[18:33]
	s_waitcnt lgkmcnt(3)
	v_mfma_f32_32x32x16_bf16 v[18:33], v[224:227], v[142:145], v[18:33]
	s_waitcnt lgkmcnt(2)
	v_mfma_f32_32x32x16_bf16 v[18:33], v[228:231], v[138:141], v[18:33]
	s_waitcnt lgkmcnt(1)
	v_mfma_f32_32x32x16_bf16 v[18:33], v[232:235], v[134:137], v[18:33]
	s_waitcnt lgkmcnt(0)
	v_mfma_f32_32x32x16_bf16 v[18:33], v[236:239], v[130:133], v[18:33]
.LBB0_180:
	s_add_i32 s2, s13, 1
	s_cmp_lt_i32 s2, s27
	s_cselect_b64 s[2:3], -1, 0
	s_cmp_gt_i32 s13, -2
	s_cselect_b64 s[24:25], -1, 0
	s_and_b64 s[56:57], s[24:25], s[2:3]
	v_cndmask_b32_e64 v51, 0, 1, s[56:57]
	v_mov_b32_e32 v50, 0
	v_cmp_ne_u32_e64 s[46:47], 1, v51
	s_andn2_b64 vcc, exec, s[56:57]
	v_mov_b32_e32 v66, 0
	v_mov_b32_e32 v67, 0
	v_mov_b32_e32 v68, 0
	v_mov_b32_e32 v69, 0
	v_mov_b32_e32 v70, 0
	v_mov_b32_e32 v71, 0
	v_mov_b32_e32 v72, 0
	v_mov_b32_e32 v73, 0
	v_mov_b32_e32 v74, 0
	v_mov_b32_e32 v75, 0
	v_mov_b32_e32 v76, 0
	v_mov_b32_e32 v77, 0
	v_mov_b32_e32 v78, 0
	v_mov_b32_e32 v79, 0
	v_mov_b32_e32 v80, 0
	v_mov_b32_e32 v81, 0
	s_mov_b32 s36, s91
	s_mov_b32 s37, s78
	s_cbranch_vccnz .LBB0_182
	ds_read_b128 v[208:211], v189 offset:24576
	v_lshl_add_u32 v240, v190, 4, v175
	ds_read_b128 v[212:215], v240 offset:24576
	v_lshl_add_u32 v240, v188, 4, v175
	ds_read_b128 v[216:219], v240 offset:24576
	v_lshl_add_u32 v240, v187, 4, v175
	ds_read_b128 v[220:223], v240 offset:24576
	v_lshl_add_u32 v240, v186, 4, v175
	ds_read_b128 v[224:227], v240 offset:24576
	v_lshl_add_u32 v240, v185, 4, v175
	ds_read_b128 v[228:231], v240 offset:24576
	v_lshl_add_u32 v240, v177, 4, v175
	ds_read_b128 v[232:235], v240 offset:24576
	v_lshl_add_u32 v240, v176, 4, v175
	ds_read_b128 v[236:239], v240 offset:24576
	s_waitcnt lgkmcnt(7)
	v_mfma_f32_32x32x16_bf16 v[66:81], v[208:211], v[158:161], 0
	s_waitcnt lgkmcnt(6)
	v_mfma_f32_32x32x16_bf16 v[66:81], v[212:215], v[154:157], v[66:81]
	s_waitcnt lgkmcnt(5)
	v_mfma_f32_32x32x16_bf16 v[66:81], v[216:219], v[150:153], v[66:81]
	s_waitcnt lgkmcnt(4)
	v_mfma_f32_32x32x16_bf16 v[66:81], v[220:223], v[146:149], v[66:81]
	s_waitcnt lgkmcnt(3)
	v_mfma_f32_32x32x16_bf16 v[66:81], v[224:227], v[142:145], v[66:81]
	s_waitcnt lgkmcnt(2)
	v_mfma_f32_32x32x16_bf16 v[66:81], v[228:231], v[138:141], v[66:81]
	s_waitcnt lgkmcnt(1)
	v_mfma_f32_32x32x16_bf16 v[66:81], v[232:235], v[134:137], v[66:81]
	s_waitcnt lgkmcnt(0)
	v_mfma_f32_32x32x16_bf16 v[66:81], v[236:239], v[130:133], v[66:81]
.LBB0_182:
	s_add_i32 s2, s13, 2
	s_cmp_lt_i32 s2, s27
	s_cselect_b64 s[2:3], -1, 0
	s_cmp_gt_i32 s13, -3
	s_cselect_b64 s[24:25], -1, 0
	s_and_b64 s[24:25], s[24:25], s[2:3]
	v_cndmask_b32_e64 v51, 0, 1, s[24:25]
	v_cmp_ne_u32_e64 s[48:49], 1, v51
	s_andn2_b64 vcc, exec, s[24:25]
	v_mov_b32_e32 v51, 0
	v_mov_b32_e32 v52, 0
	v_mov_b32_e32 v53, 0
	v_mov_b32_e32 v54, 0
	v_mov_b32_e32 v55, 0
	v_mov_b32_e32 v56, 0
	v_mov_b32_e32 v57, 0
	v_mov_b32_e32 v58, 0
	v_mov_b32_e32 v59, 0
	v_mov_b32_e32 v60, 0
	v_mov_b32_e32 v61, 0
	v_mov_b32_e32 v62, 0
	v_mov_b32_e32 v63, 0
	v_mov_b32_e32 v64, 0
	v_mov_b32_e32 v65, 0
	s_mov_b32 s78, s58
	s_mov_b32 s91, s59
	s_cbranch_vccnz .LBB0_184
	ds_read_b128 v[208:211], v189 offset:32768
	v_lshl_add_u32 v240, v190, 4, v175
	ds_read_b128 v[212:215], v240 offset:32768
	v_lshl_add_u32 v240, v188, 4, v175
	ds_read_b128 v[216:219], v240 offset:32768
	v_lshl_add_u32 v240, v187, 4, v175
	ds_read_b128 v[220:223], v240 offset:32768
	v_lshl_add_u32 v240, v186, 4, v175
	ds_read_b128 v[224:227], v240 offset:32768
	v_lshl_add_u32 v240, v185, 4, v175
	ds_read_b128 v[228:231], v240 offset:32768
	v_lshl_add_u32 v240, v177, 4, v175
	ds_read_b128 v[232:235], v240 offset:32768
	v_lshl_add_u32 v240, v176, 4, v175
	ds_read_b128 v[236:239], v240 offset:32768
	s_waitcnt lgkmcnt(7)
	v_mfma_f32_32x32x16_bf16 v[50:65], v[208:211], v[158:161], 0
	s_waitcnt lgkmcnt(6)
	v_mfma_f32_32x32x16_bf16 v[50:65], v[212:215], v[154:157], v[50:65]
	s_waitcnt lgkmcnt(5)
	v_mfma_f32_32x32x16_bf16 v[50:65], v[216:219], v[150:153], v[50:65]
	s_waitcnt lgkmcnt(4)
	v_mfma_f32_32x32x16_bf16 v[50:65], v[220:223], v[146:149], v[50:65]
	s_waitcnt lgkmcnt(3)
	v_mfma_f32_32x32x16_bf16 v[50:65], v[224:227], v[142:145], v[50:65]
	s_waitcnt lgkmcnt(2)
	v_mfma_f32_32x32x16_bf16 v[50:65], v[228:231], v[138:141], v[50:65]
	s_waitcnt lgkmcnt(1)
	v_mfma_f32_32x32x16_bf16 v[50:65], v[232:235], v[134:137], v[50:65]
	s_waitcnt lgkmcnt(0)
	v_mfma_f32_32x32x16_bf16 v[50:65], v[236:239], v[130:133], v[50:65]
